# WKV scan prep waves: per-chunk r/k/v/e/a global loads issued two chunks ahead (two staging register sets, counted vmcnt(7)) instead of one
# baseline (speedup 1.0000x reference)
.LBB0_543:
	s_or_b64 exec, exec, s[2:3]
	v_or_b32_e32 v104, 0x4000, v104
	v_lshlrev_b64 v[2:3], 1, v[104:105]
	v_lshl_add_u64 v[16:17], s[24:25], 0, v[2:3]
	v_lshl_add_u64 v[18:19], s[26:27], 0, v[2:3]
	v_lshl_add_u64 v[20:21], s[28:29], 0, v[2:3]
	v_lshl_add_u64 v[22:23], s[30:31], 0, v[2:3]
	global_load_dwordx2 v[108:109], v[16:17], off
	global_load_dwordx2 v[110:111], v[18:19], off
	global_load_dwordx2 v[112:113], v[20:21], off
	global_load_dwordx2 v[114:115], v[22:23], off
	v_lshl_add_u64 v[2:3], s[34:35], 0, v[2:3]
	global_load_dwordx2 v[116:117], v[2:3], off
	v_add_u32_e32 v104, 0x4000, v104
	v_lshlrev_b64 v[2:3], 1, v[104:105]
	v_lshl_add_u64 v[16:17], s[24:25], 0, v[2:3]
	v_lshl_add_u64 v[18:19], s[26:27], 0, v[2:3]
	v_lshl_add_u64 v[20:21], s[28:29], 0, v[2:3]
	v_lshl_add_u64 v[22:23], s[30:31], 0, v[2:3]
	global_load_dwordx2 v[198:199], v[16:17], off
	global_load_dwordx2 v[200:201], v[18:19], off
	global_load_dwordx2 v[202:203], v[20:21], off
	global_load_dwordx2 v[204:205], v[22:23], off
	v_lshl_add_u64 v[2:3], s[34:35], 0, v[2:3]
	global_load_dwordx2 v[206:207], v[2:3], off
	v_mov_b32_e32 v16, v0

.LBB0_547:
	s_and_b32 s93, s92, 1
	s_mov_b64 s[4:5], -1
	s_and_b64 vcc, exec, s[42:43]
	s_cbranch_vccz .LBB0_641
	s_cmpk_lt_u32 s92, 3
	s_cbranch_scc1 .Lscan_w0
	s_cmpk_gt_u32 s92, 0xfc
	s_cbranch_scc1 .Lscan_w0
	s_waitcnt vmcnt(7)
	s_branch .Lscan_w1

.Lscan_w1:
	s_cmp_eq_u32 s93, 0
	s_cbranch_scc0 .Lscan_odd
	v_mov_b64_e32 v[94:95], v[108:109]
	v_mov_b64_e32 v[96:97], v[110:111]
	v_mov_b64_e32 v[98:99], v[112:113]
	v_mov_b64_e32 v[100:101], v[114:115]
	v_mov_b64_e32 v[102:103], v[116:117]
	s_cmpk_gt_u32 s92, 0xfc
	s_cbranch_scc1 .Lscan_noload
	s_mov_b64 s[4:5], 0x4000
	v_lshl_add_u64 v[104:105], v[104:105], 0, s[4:5]
	v_lshlrev_b64 v[24:25], 1, v[104:105]
	v_lshl_add_u64 v[26:27], s[24:25], 0, v[24:25]
	v_lshl_add_u64 v[28:29], s[26:27], 0, v[24:25]
	v_lshl_add_u64 v[30:31], s[28:29], 0, v[24:25]
	v_lshl_add_u64 v[32:33], s[30:31], 0, v[24:25]
	global_load_dwordx2 v[108:109], v[26:27], off
	global_load_dwordx2 v[110:111], v[28:29], off
	global_load_dwordx2 v[112:113], v[30:31], off
	global_load_dwordx2 v[114:115], v[32:33], off
	v_lshl_add_u64 v[24:25], s[34:35], 0, v[24:25]
	global_load_dwordx2 v[116:117], v[24:25], off
	s_branch .Lscan_noload
.Lscan_odd:
	v_mov_b64_e32 v[94:95], v[198:199]
	v_mov_b64_e32 v[96:97], v[200:201]
	v_mov_b64_e32 v[98:99], v[202:203]
	v_mov_b64_e32 v[100:101], v[204:205]
	v_mov_b64_e32 v[102:103], v[206:207]
	s_cmpk_gt_u32 s92, 0xfc
	s_cbranch_scc1 .Lscan_noload
	s_mov_b64 s[4:5], 0x4000
	v_lshl_add_u64 v[104:105], v[104:105], 0, s[4:5]
	v_lshlrev_b64 v[24:25], 1, v[104:105]
	v_lshl_add_u64 v[26:27], s[24:25], 0, v[24:25]
	v_lshl_add_u64 v[28:29], s[26:27], 0, v[24:25]
	v_lshl_add_u64 v[30:31], s[28:29], 0, v[24:25]
	v_lshl_add_u64 v[32:33], s[30:31], 0, v[24:25]
	global_load_dwordx2 v[198:199], v[26:27], off
	global_load_dwordx2 v[200:201], v[28:29], off
	global_load_dwordx2 v[202:203], v[30:31], off
	global_load_dwordx2 v[204:205], v[32:33], off
	v_lshl_add_u64 v[24:25], s[34:35], 0, v[24:25]
	global_load_dwordx2 v[206:207], v[24:25], off
